# v11 plus SGPR-base next-unit gathers issued at the start of S1 (earlier prefetch)
# baseline (speedup 1.0000x reference)
.LBB0_698:
	v_cndmask_b32_e64 v29, v34, 0, s[24:25]
	v_readlane_b32 s80, v233, 39
	v_add_f32_e32 v34, v35, v29
	v_readlane_b32 s81, v233, 40
	v_readlane_b32 s0, v233, 41
	v_readlane_b32 s1, v233, 42
	v_cndmask_b32_e64 v29, v29, v34, s[80:81]
	v_add_f32_e32 v32, v32, v29
	v_cndmask_b32_e64 v29, v29, v32, s[0:1]
	v_readlane_b32 s0, v233, 43
	v_add_f32_e32 v32, v33, v29
	v_readlane_b32 s1, v233, 44
	s_nop 1
	v_cndmask_b32_e64 v29, v29, v32, s[0:1]
	v_readlane_b32 s0, v233, 45
	v_add_f32_e32 v30, v30, v29
	v_readlane_b32 s1, v233, 46
	s_nop 0
	s_nop 0
	v_cndmask_b32_e64 v29, v29, v30, s[0:1]
	v_readlane_b32 s0, v233, 47
	v_add_f32_e32 v31, v31, v29
	v_readlane_b32 s1, v233, 48
	s_nop 1
	v_cndmask_b32_e64 v29, v29, v31, s[0:1]
	v_add_f32_e32 v18, v18, v29
	s_nop 1
	s_nop 0
	v_readlane_b32 s0, v233, 49
	v_readlane_b32 s1, v233, 50
	s_nop 1
	v_cndmask_b32_e64 v18, v29, v18, s[0:1]
	v_readlane_b32 s0, v233, 51
	v_add_f32_e32 v19, v19, v18
	v_readlane_b32 s1, v233, 52
	s_nop 1
	v_cndmask_b32_e64 v18, v18, v19, s[0:1]
	v_sqrt_f32_e32 v19, s46
	s_nop 0
	v_max_f32_e32 v19, 0x2b8cbccc, v19
	v_rcp_f32_e32 v19, v19
	s_nop 0
	v_mul_f32_e32 v19, v112, v19
	v_add_f32_e32 v109, v109, v18
	v_mul_f32_e32 v17, v19, v17
	v_sqrt_f32_e32 v29, s19
	s_nop 0
	v_max_f32_e32 v29, 0x2b8cbccc, v29
	v_rcp_f32_e32 v29, v29
	s_nop 0
	v_mul_f32_e32 v29, v111, v29
	v_mul_f32_e32 v15, v29, v15
	s_nop 0
	v_sqrt_f32_e32 v30, s18
	s_nop 0
	v_max_f32_e32 v30, 0x2b8cbccc, v30
	v_rcp_f32_e32 v30, v30
	s_nop 0
	v_mul_f32_e32 v114, v110, v30
	v_mul_f32_e32 v16, v114, v16
	s_nop 0
	v_sqrt_f32_e32 v30, s17
	s_nop 0
	v_max_f32_e32 v30, 0x2b8cbccc, v30
	v_rcp_f32_e32 v30, v30
	s_nop 0
	v_mul_f32_e32 v104, v104, v30
	v_mul_f32_e32 v14, v104, v14
	s_nop 0
	v_sqrt_f32_e32 v30, s9
	s_nop 0
	v_max_f32_e32 v30, 0x2b8cbccc, v30
	v_rcp_f32_e32 v30, v30
	s_nop 0
	v_mul_f32_e32 v100, v100, v30
	v_mul_f32_e32 v13, v100, v13
	s_nop 0
	v_sqrt_f32_e32 v30, s8
	s_nop 0
	v_max_f32_e32 v30, 0x2b8cbccc, v30
	v_rcp_f32_e32 v30, v30
	s_nop 0
	v_mul_f32_e32 v115, v99, v30
	v_lshlrev_b32_e32 v110, 16, v61
	v_mov_b32_e32 v111, s6
	v_mul_f32_e32 v11, v115, v11
	s_nop 0
	v_and_b32_e32 v31, 0xffff0000, v88
	v_sqrt_f32_e32 v30, s7
	s_nop 0
	v_max_f32_e32 v30, 0x2b8cbccc, v30
	v_rcp_f32_e32 v30, v30
	s_nop 0
	v_mul_f32_e32 v116, v98, v30
	v_lshlrev_b32_e32 v30, 16, v88
	v_lshlrev_b32_e32 v33, 16, v54
	v_lshlrev_b32_e32 v35, 16, v52
	v_lshlrev_b32_e32 v34, 16, v45
	v_mov_b32_e32 v32, v31
	v_pk_add_f32 v[30:31], v[30:31], v[34:35] neg_lo:[0,1] neg_hi:[0,1]
	v_pk_add_f32 v[98:99], v[34:35], v[32:33] neg_lo:[0,1] neg_hi:[0,1]
	v_pk_fma_f32 v[30:31], v[24:25], v[30:31], v[34:35] op_sel_hi:[0,1,1]
	v_pk_fma_f32 v[34:35], v[98:99], v[24:25], v[32:33] op_sel_hi:[1,0,1]
	v_mul_f32_e32 v32, s6, v79
	v_cmp_lt_f32_e32 vcc, s6, v78
	v_lshlrev_b32_e32 v99, 16, v66
	v_lshlrev_b32_e32 v98, 16, v56
	v_cndmask_b32_e32 v112, v111, v32, vcc
	v_sqrt_f32_e32 v113, v112
	v_lshlrev_b32_e32 v111, 16, v71
	v_pk_mov_b32 v[32:33], v[32:33], v[110:111] op_sel:[1,0]
	v_mul_f32_e32 v12, v116, v12
	v_add_u32_e32 v117, -1, v113
	v_fma_f32 v118, -v117, v113, v112
	v_cmp_ge_f32_e64 s[0:1], 0, v118
	v_add_u32_e32 v118, 1, v113
	v_pk_add_f32 v[32:33], v[32:33], v[98:99] neg_lo:[0,1] neg_hi:[0,1]
	v_cndmask_b32_e64 v117, v113, v117, s[0:1]
	v_fma_f32 v113, -v118, v113, v112
	v_cmp_lt_f32_e64 s[0:1], 0, v113
	v_pk_fma_f32 v[32:33], v[32:33], v[24:25], v[98:99] op_sel_hi:[1,0,1]
	s_nop 0
	v_cndmask_b32_e64 v113, v117, v118, s[0:1]
	v_mul_f32_e32 v117, 0x37800000, v113
	v_cndmask_b32_e32 v113, v113, v117, vcc
	v_cmp_class_f32_e32 vcc, v112, v77
	s_nop 1
	v_cndmask_b32_e32 v112, v113, v112, vcc
	v_max_f32_e32 v117, 0x2b8cbccc, v112
	v_div_scale_f32 v118, s[0:1], v117, v117, v97
	v_pk_add_f32 v[112:113], v[98:99], v[110:111] neg_lo:[0,1] neg_hi:[0,1]
	s_nop 0
	v_pk_fma_f32 v[98:99], v[112:113], v[24:25], v[110:111] op_sel_hi:[1,0,1]
	v_sqrt_f32_e32 v110, s6
	s_nop 0
	v_max_f32_e32 v110, 0x2b8cbccc, v110
	v_rcp_f32_e32 v110, v110
	s_nop 0
	v_mul_f32_e32 v97, v97, v110
	v_mul_f32_e32 v110, 0x3fb8aa3b, v18
	v_exp_f32_e32 v111, v110
	v_mul_f32_e32 v110, 0x3fb8aa3b, v109
	v_exp_f32_e32 v112, v110
	v_mul_f32_e32 v109, 0xbfb8aa3b, v109
	v_exp_f32_e32 v110, v109
	v_mul_f32_e32 v10, v97, v10
	v_mul_f32_e64 v97, v111, -v97
	v_mul_f32_e32 v96, v96, v112
	v_cvt_pk_bf16_f32 v109, v97, s0
	v_cvt_pk_bf16_f32 v96, v96, s0
	v_mul_f32_e32 v97, v10, v110
	v_mul_f32_e32 v111, v0, v110
	v_cvt_pk_bf16_f32 v113, v30, v31
	v_add_f32_e32 v31, v108, v18
	v_cvt_pk_bf16_f32 v97, v97, s0
	v_cvt_pk_bf16_f32 v111, v111, s0
	ds_write_b16 v204, v109
	ds_write_b16 v204, v96 offset:9216
	ds_write_b16 v204, v97 offset:18432
	ds_write_b16 v204, v111 offset:27648
	v_mul_f32_e32 v96, 0x3fb8aa3b, v31
	v_mul_f32_e32 v31, 0xbfb8aa3b, v31
	v_exp_f32_e32 v97, v96
	v_exp_f32_e32 v96, v31
	v_mul_f32_e64 v31, v112, -v116
	v_cvt_pk_bf16_f32 v112, v34, v35
	v_add_f32_e32 v34, v107, v18
	v_mul_f32_e32 v111, v4, v96
	v_mul_f32_e32 v35, 0x3fb8aa3b, v34
	v_cvt_pk_bf16_f32 v31, v31, s0
	v_mul_f32_e32 v94, v94, v97
	v_mul_f32_e32 v108, v12, v96
	v_cvt_pk_bf16_f32 v111, v111, s0
	v_exp_f32_e32 v35, v35
	v_mul_f32_e32 v34, 0xbfb8aa3b, v34
	v_cvt_pk_bf16_f32 v94, v94, s0
	v_cvt_pk_bf16_f32 v108, v108, s0
	ds_write_b16 v204, v31 offset:144
	ds_write_b16 v204, v94 offset:9360
	ds_write_b16 v204, v108 offset:18576
	ds_write_b16 v204, v111 offset:27792
	v_exp_f32_e32 v111, v34
	v_mul_f32_e64 v34, v97, -v115
	v_cvt_pk_bf16_f32 v94, v34, s0
	v_mul_f32_e32 v34, v92, v35
	v_cvt_pk_bf16_f32 v34, v34, s0
	v_mul_f32_e32 v92, v11, v111
	v_mul_f32_e32 v97, v1, v111
	v_cvt_pk_bf16_f32 v92, v92, s0
	v_cvt_pk_bf16_f32 v97, v97, s0
	ds_write_b16 v204, v94 offset:288
	ds_write_b16 v204, v34 offset:9504
	ds_write_b16 v204, v92 offset:18720
	ds_write_b16 v204, v97 offset:27936
	v_add_f32_e32 v34, v106, v18
	v_mul_f32_e32 v92, 0x3fb8aa3b, v34
	v_exp_f32_e32 v92, v92
	v_mul_f32_e32 v34, 0xbfb8aa3b, v34
	v_exp_f32_e32 v97, v34
	v_mul_f32_e64 v34, v35, -v100
	v_cvt_pk_bf16_f32 v100, v34, s0
	v_mul_f32_e32 v34, v90, v92
	v_cvt_pk_bf16_f32 v34, v34, s0
	v_mul_f32_e32 v35, v13, v97
	v_mul_f32_e32 v90, v5, v97
	v_cvt_pk_bf16_f32 v35, v35, s0
	v_cvt_pk_bf16_f32 v90, v90, s0
	ds_write_b16 v204, v100 offset:432
	ds_write_b16 v204, v34 offset:9648
	ds_write_b16 v204, v35 offset:18864
	ds_write_b16 v204, v90 offset:28080
	v_add_f32_e32 v34, v105, v18
	v_mul_f32_e32 v35, 0x3fb8aa3b, v34
	v_exp_f32_e32 v35, v35
	v_mul_f32_e32 v34, 0xbfb8aa3b, v34
	v_exp_f32_e32 v34, v34
	v_mul_f32_e64 v90, v92, -v104
	v_cvt_pk_bf16_f32 v105, v32, v33
	v_add_f32_e32 v32, v103, v18
	v_cvt_pk_bf16_f32 v92, v90, s0
	v_mul_f32_e32 v90, v95, v35
	v_mul_f32_e32 v33, 0x3fb8aa3b, v32
	v_cvt_pk_bf16_f32 v90, v90, s0
	v_mul_f32_e32 v95, v14, v34
	v_mul_f32_e32 v104, v6, v34
	v_exp_f32_e32 v33, v33
	v_mul_f32_e32 v32, 0xbfb8aa3b, v32
	v_cvt_pk_bf16_f32 v95, v95, s0
	v_cvt_pk_bf16_f32 v104, v104, s0
	ds_write_b16 v204, v92 offset:576
	ds_write_b16 v204, v90 offset:9792
	ds_write_b16 v204, v95 offset:19008
	ds_write_b16 v204, v104 offset:28224
	v_exp_f32_e32 v90, v32
	v_mul_f32_e64 v32, v35, -v114
	v_mul_f32_e32 v35, v93, v33
	v_cvt_pk_bf16_f32 v32, v32, s0
	v_cvt_pk_bf16_f32 v35, v35, s0
	v_mul_f32_e32 v93, v16, v90
	v_mul_f32_e32 v95, v8, v90
	v_cvt_pk_bf16_f32 v93, v93, s0
	v_cvt_pk_bf16_f32 v95, v95, s0
	ds_write_b16 v204, v32 offset:720
	ds_write_b16 v204, v35 offset:9936
	ds_write_b16 v204, v93 offset:19152
	ds_write_b16 v204, v95 offset:28368
	v_add_f32_e32 v35, v102, v18
	v_mul_f32_e32 v93, 0x3fb8aa3b, v35
	v_exp_f32_e32 v93, v93
	v_mul_f32_e32 v35, 0xbfb8aa3b, v35
	v_exp_f32_e32 v35, v35
	v_mul_f32_e64 v29, v33, -v29
	v_mul_f32_e32 v33, v91, v93
	v_cvt_pk_bf16_f32 v29, v29, s0
	v_cvt_pk_bf16_f32 v33, v33, s0
	v_mul_f32_e32 v91, v15, v35
	v_mul_f32_e32 v95, v7, v35
	v_add_f32_e32 v18, v101, v18
	v_cvt_pk_bf16_f32 v91, v91, s0
	v_cvt_pk_bf16_f32 v95, v95, s0
	ds_write_b16 v204, v29 offset:864
	ds_write_b16 v204, v33 offset:10080
	ds_write_b16 v204, v91 offset:19296
	ds_write_b16 v204, v95 offset:28512
	v_mul_f32_e32 v33, 0x3fb8aa3b, v18
	v_exp_f32_e32 v33, v33
	v_mul_f32_e32 v18, 0xbfb8aa3b, v18
	v_exp_f32_e32 v91, v18
	v_mul_f32_e64 v18, v93, -v19
	v_mul_f32_e32 v19, v89, v33
	v_cvt_pk_bf16_f32 v18, v18, s0
	v_cvt_pk_bf16_f32 v19, v19, s0
	v_mul_f32_e32 v33, v17, v91
	v_mul_f32_e32 v89, v9, v91
	v_cvt_pk_bf16_f32 v33, v33, s0
	v_cvt_pk_bf16_f32 v89, v89, s0
	ds_write_b16 v204, v18 offset:1008
	ds_write_b16 v204, v19 offset:10224
	ds_write_b16 v204, v33 offset:19440
	ds_write_b16 v204, v89 offset:28656
	v_perm_b32 v30, v31, v109, s96
	v_perm_b32 v31, v100, v94, s96
	v_perm_b32 v33, v18, v29, s96
	v_perm_b32 v32, v32, v92, s96
	v_pk_mul_f32 v[18:19], v[2:3], v[110:111] op_sel_hi:[0,1]
	ds_write_b128 v159, v[30:33] offset:36864
	v_pk_mul_f32 v[30:31], v[2:3], v[96:97] op_sel_hi:[0,1]
	v_pk_mul_f32 v[10:11], v[10:11], v[18:19]
	v_pk_mul_f32 v[0:1], v[0:1], v[18:19]
	v_cvt_pk_bf16_f32 v32, v10, v11
	v_pk_mul_f32 v[10:11], v[12:13], v[30:31]
	v_cvt_pk_bf16_f32 v98, v98, v99
	v_cvt_pk_bf16_f32 v10, v10, v11
	v_perm_b32 v11, v10, v32, s97
	v_perm_b32 v10, v10, v32, s96
	v_pk_mul_f32 v[32:33], v[2:3], v[34:35] op_sel_hi:[0,1]
	v_pk_mul_f32 v[34:35], v[2:3], v[90:91] op_sel_hi:[0,1]
	v_pk_mul_f32 v[12:13], v[14:15], v[32:33]
	s_mov_b64 s[0:1], -1
	v_cvt_pk_bf16_f32 v2, v12, v13
	v_pk_mul_f32 v[12:13], v[16:17], v[34:35]
	s_and_b64 vcc, exec, s[80:81]
	v_cvt_pk_bf16_f32 v12, v12, v13
	v_perm_b32 v13, v12, v2, s97
	v_perm_b32 v12, v12, v2, s96
	v_cvt_pk_bf16_f32 v2, v0, v1
	v_pk_mul_f32 v[0:1], v[4:5], v[30:31]
	ds_write_b128 v159, v[10:13] offset:46080
	v_cvt_pk_bf16_f32 v0, v0, v1
	v_perm_b32 v5, v0, v2, s97
	v_perm_b32 v4, v0, v2, s96
	v_pk_mul_f32 v[0:1], v[6:7], v[32:33]
	v_mov_b32_e32 v12, s55
	v_cvt_pk_bf16_f32 v2, v0, v1
	v_pk_mul_f32 v[0:1], v[8:9], v[34:35]
	s_nop 0
	v_cvt_pk_bf16_f32 v0, v0, v1
	v_perm_b32 v7, v0, v2, s97
	v_perm_b32 v6, v0, v2, s96
	ds_write_b128 v159, v[4:7] offset:55296
	v_perm_b32 v5, v112, v113, s97
	v_perm_b32 v4, v112, v113, s96
	v_perm_b32 v7, v98, v105, s97
	v_perm_b32 v6, v98, v105, s96
	ds_write_b128 v159, v[4:7] offset:64512
	s_waitcnt lgkmcnt(0)
	s_barrier
	s_nop 0
	s_cmpk_gt_i32 s79, 0xfff
	s_cbranch_scc1 .Lpa_pf_skip
	s_and_b32 s4, s79, 0x7f
	s_ashr_i32 s8, s79, 11
	s_ashr_i32 s9, s8, 31
	s_lshl_b32 s5, s4, 6
	s_lshl_b64 s[8:9], s[8:9], 13
	s_add_i32 s5, s5, s33
	s_add_u32 s6, s8, s5
	s_addc_u32 s7, s9, 0
	s_lshr_b32 s5, s79, 1
	s_and_b32 s5, s5, 0x3c0
	v_add_u32_e32 v0, s5, v207
	s_mul_i32 s94, s7, 0x3c00
	s_mul_hi_u32 s95, s6, 0x3c00
	s_add_i32 s95, s95, s94
	s_mul_i32 s94, s6, 0x3c00
	v_readlane_b32 s8, v233, 14
	v_readlane_b32 s9, v233, 15
	v_lshlrev_b32_e32 v1, 1, v0
	v_add_u32_e32 v2, 0x1000, v1
	s_add_u32 s94, s8, s94
	s_addc_u32 s95, s9, s95
	s_lshl_b64 s[6:7], s[6:7], 11
	v_readlane_b32 s8, v233, 24
	v_readlane_b32 s9, v233, 25
	v_lshlrev_b32_e32 v4, 2, v0
	v_add_u32_e32 v5, 0x1000, v4
	s_add_u32 s90, s2, s6
	s_addc_u32 s91, s3, s7
	s_add_u32 s92, s8, s6
	s_addc_u32 s93, s9, s7
	v_add_u32_e32 v6, 0x2000, v4
	global_load_ushort v37, v1, s[94:95]
	global_load_ushort v27, v1, s[94:95] offset:2048
	global_load_ushort v45, v2, s[94:95]
	global_load_ushort v36, v1, s[90:91]
	global_load_ushort v25, v1, s[92:93]
	s_add_u32 s6, s94, 0x3c00
	s_addc_u32 s7, s95, 0
	global_load_ushort v39, v1, s[6:7]
	global_load_ushort v38, v1, s[6:7] offset:2048
	global_load_ushort v47, v2, s[6:7]
	global_load_ushort v41, v1, s[90:91] offset:2048
	global_load_ushort v40, v1, s[92:93] offset:2048
	s_add_u32 s6, s94, 0x7800
	s_addc_u32 s7, s95, 0
	s_add_u32 s90, s90, 0x1000
	s_addc_u32 s91, s91, 0
	s_add_u32 s92, s92, 0x1000
	s_addc_u32 s93, s93, 0
	global_load_ushort v46, v1, s[6:7]
	global_load_ushort v43, v1, s[6:7] offset:2048
	global_load_ushort v52, v2, s[6:7]
	global_load_ushort v44, v1, s[90:91]
	global_load_ushort v42, v1, s[92:93]
	s_add_u32 s6, s94, 0xb400
	s_addc_u32 s7, s95, 0
	global_load_ushort v48, v1, s[6:7]
	global_load_ushort v50, v1, s[6:7] offset:2048
	global_load_ushort v54, v2, s[6:7]
	global_load_ushort v51, v1, s[90:91] offset:2048
	global_load_ushort v49, v1, s[92:93] offset:2048
	s_add_u32 s6, s94, 0xf000
	s_addc_u32 s7, s95, 0
	s_add_u32 s90, s90, 0x1000
	s_addc_u32 s91, s91, 0
	s_add_u32 s92, s92, 0x1000
	s_addc_u32 s93, s93, 0
	global_load_ushort v55, v1, s[6:7]
	global_load_ushort v53, v1, s[6:7] offset:2048
	global_load_ushort v56, v2, s[6:7]
	global_load_ushort v57, v1, s[90:91]
	global_load_ushort v58, v1, s[92:93]
	s_add_u32 s6, s94, 0x12c00
	s_addc_u32 s7, s95, 0
	global_load_ushort v62, v1, s[6:7]
	global_load_ushort v59, v1, s[6:7] offset:2048
	global_load_ushort v61, v2, s[6:7]
	global_load_ushort v63, v1, s[90:91] offset:2048
	global_load_ushort v60, v1, s[92:93] offset:2048
	s_add_u32 s6, s94, 0x16800
	s_addc_u32 s7, s95, 0
	s_add_u32 s90, s90, 0x1000
	s_addc_u32 s91, s91, 0
	s_add_u32 s92, s92, 0x1000
	s_addc_u32 s93, s93, 0
	global_load_ushort v64, v1, s[6:7]
	global_load_ushort v65, v1, s[6:7] offset:2048
	global_load_ushort v66, v2, s[6:7]
	global_load_ushort v68, v1, s[90:91]
	global_load_ushort v67, v1, s[92:93]
	s_add_u32 s6, s94, 0x1a400
	s_addc_u32 s7, s95, 0
	global_load_ushort v72, v1, s[6:7]
	global_load_ushort v70, v1, s[6:7] offset:2048
	global_load_ushort v71, v2, s[6:7]
	global_load_ushort v74, v1, s[90:91] offset:2048
	global_load_ushort v73, v1, s[92:93] offset:2048
	v_readlane_b32 s5, v233, 5
	s_or_b32 s4, s4, s5
	s_cmp_eq_u32 s4, 0
	s_cbranch_scc1 .LBB0_787
	s_add_u32 s6, s94, 0xffffc400
	s_addc_u32 s7, s95, -1
	global_load_ushort v75, v1, s[6:7]
	global_load_ushort v76, v1, s[6:7] offset:2048
	global_load_ushort v88, v2, s[6:7]
	s_branch .LBB0_788

.LBB0_788:
	global_load_dword v84, v4, s[40:41]
	global_load_dword v22, v5, s[40:41]
	global_load_dword v24, v6, s[40:41]
	s_load_dwordx2 s[6:7], s[82:83], 0x98
	global_load_dword v85, v4, s[12:13]
	global_load_dword v26, v4, s[14:15]
	s_waitcnt lgkmcnt(0)
	global_load_dword v86, v4, s[6:7]
.Lpa_pf_skip:
	v_and_b32_e32 v0, 15, v28
	v_and_b32_e32 v1, -16, v28
	v_mad_u32_u24 v12, v0, s76, v12
	v_add_u32_e32 v30, v12, v1
	ds_read_b128 v[8:11], v140
	ds_read_b128 v[4:7], v140 offset:64
	ds_read_b128 v[16:19], v156
	ds_read_b128 v[12:15], v156 offset:64
	v_ashrrev_i32_e32 v2, 4, v28
	v_lshlrev_b32_e32 v29, 2, v2
	v_lshlrev_b32_e32 v2, 3, v2
	v_add_u32_e32 v33, s56, v2
	v_or_b32_e32 v89, v29, v69
	s_cbranch_vccz .LBB0_700
	s_waitcnt lgkmcnt(1)
	v_mfma_f32_16x16x32_bf16 v[94:97], v[16:19], v[8:11], 0
	s_mov_b64 s[0:1], 0
	s_waitcnt lgkmcnt(0)
	v_mfma_f32_16x16x32_bf16 v[94:97], v[12:15], v[4:7], v[94:97]
	s_nop 7
	v_bfi_b32 v35, v196, v94, v206
	v_and_b32_e32 v90, v166, v95
	v_cvt_pk_bf16_f32 v90, v35, v90
	v_and_b32_e32 v91, v199, v96
	v_and_b32_e32 v93, v202, v97
	v_cvt_pk_bf16_f32 v91, v91, v93
	ds_write_b64 v151, v[90:91]

.LBB0_784:
	s_cmpk_gt_i32 s79, 0xfff
	s_waitcnt lgkmcnt(0)
	s_barrier
.LBB0_789:
	v_and_b32_e32 v0, 15, v207
	v_or_b32_e32 v1, s68, v0
	v_and_b32_e32 v2, -16, v207
	v_mul_u32_u24_e32 v0, 0x90, v0
	v_add3_u32 v29, 0, v0, v2
	ds_read_b128 v[4:7], v29
	v_mul_u32_u24_e32 v0, 0x90, v1
	v_add3_u32 v1, s66, v0, v2
	ds_read_b128 v[8:11], v29 offset:64
	ds_read_b128 v[12:15], v1
	ds_read_b128 v[16:19], v1 offset:64
	v_ashrrev_i32_e32 v1, 1, v207
	v_and_b32_e32 v1, -8, v1
	v_add3_u32 v2, s67, v0, v1
	s_waitcnt lgkmcnt(1)
	v_mfma_f32_16x16x32_bf16 v[4:7], v[4:7], v[12:15], 0
	v_readlane_b32 s4, v233, 43
	v_readlane_b32 s5, v233, 44
	s_mov_b64 s[0:1], -1
	s_waitcnt lgkmcnt(0)
	v_mfma_f32_16x16x32_bf16 v[4:7], v[8:11], v[16:19], v[4:7]
	s_and_b64 vcc, exec, s[4:5]
	s_nop 6
	v_cvt_pk_bf16_f32 v0, v4, v5
	v_cvt_pk_bf16_f32 v1, v6, v7
	ds_write_b64 v2, v[0:1]
	ds_read_b128 v[4:7], v29 offset:2304
	ds_read_b128 v[8:11], v29 offset:2368
	s_waitcnt lgkmcnt(1)
	v_mfma_f32_16x16x32_bf16 v[4:7], v[4:7], v[12:15], 0
	s_waitcnt lgkmcnt(0)
	v_mfma_f32_16x16x32_bf16 v[4:7], v[8:11], v[16:19], v[4:7]
	s_nop 7
	v_cvt_pk_bf16_f32 v0, v4, v5
	v_cvt_pk_bf16_f32 v1, v6, v7
	ds_write_b64 v2, v[0:1] offset:32
	ds_read_b128 v[4:7], v29 offset:4608
	ds_read_b128 v[8:11], v29 offset:4672
	s_waitcnt lgkmcnt(1)
	v_mfma_f32_16x16x32_bf16 v[4:7], v[4:7], v[12:15], 0
	s_waitcnt lgkmcnt(0)
	v_mfma_f32_16x16x32_bf16 v[4:7], v[8:11], v[16:19], v[4:7]
	s_nop 7
	v_cvt_pk_bf16_f32 v0, v4, v5
	v_cvt_pk_bf16_f32 v1, v6, v7
	ds_write_b64 v2, v[0:1] offset:64
	ds_read_b128 v[4:7], v29 offset:6912
	ds_read_b128 v[8:11], v29 offset:6976
	s_waitcnt lgkmcnt(1)
	v_mfma_f32_16x16x32_bf16 v[4:7], v[4:7], v[12:15], 0
	s_waitcnt lgkmcnt(0)
	v_mfma_f32_16x16x32_bf16 v[4:7], v[8:11], v[16:19], v[4:7]
	s_nop 7
	v_cvt_pk_bf16_f32 v0, v4, v5
	v_cvt_pk_bf16_f32 v1, v6, v7
	ds_write_b64 v2, v[0:1] offset:96
	s_waitcnt lgkmcnt(0)
	s_barrier
	s_nop 0
	v_and_b32_e32 v7, 15, v207
	v_ashrrev_i32_e32 v1, 4, v207
	v_and_b32_e32 v0, -16, v207
	v_lshlrev_b32_e32 v5, 3, v1
	v_mul_u32_u24_e32 v6, 0x90, v7
	v_mad_u32_u24 v4, v7, s76, v82
	v_mad_u32_u24 v2, v7, s76, v83
	v_mad_u32_u24 v1, v7, s76, v87
	s_cbranch_vccz .LBB0_791
	v_or_b32_e32 v8, s63, v7
	v_mul_lo_u32 v8, v8, s76
	v_add_u32_e32 v89, s69, v5
	v_add3_u32 v29, 0, v8, v0
	v_add3_u32 v30, 0, v89, v6
	ds_read_b128 v[8:11], v29 offset:18432
	ds_read_b128 v[12:15], v29 offset:18496
	ds_read_b64 v[32:33], v30 offset:9216
	s_add_i32 s0, 0, 0x17200
	v_add_u32_e32 v98, s0, v0
	v_mad_u32_u24 v99, v7, s76, v98
	ds_read_b128 v[16:19], v99
	ds_read_b64 v[34:35], v30 offset:11520
	ds_read_b64 v[94:95], v30 offset:13824
	ds_read_b64 v[96:97], v30 offset:16128
	s_waitcnt lgkmcnt(4)
	v_lshlrev_b32_e32 v30, 16, v32
	v_and_b32_e32 v31, 0xffff0000, v32
	v_lshlrev_b32_e32 v32, 16, v33
	v_and_b32_e32 v33, 0xffff0000, v33
	ds_read_b128 v[90:93], v99 offset:64
	s_add_i32 s1, 0, 0x14e00
	s_waitcnt lgkmcnt(4)
	v_mfma_f32_16x16x32_bf16 v[16:19], v[8:11], v[16:19], v[30:33]
	v_add3_u32 v89, s1, v89, v6
	v_add_u32_e32 v102, v98, v4
	v_add3_u32 v103, s0, v4, v0
	s_waitcnt lgkmcnt(0)
	v_mfma_f32_16x16x32_bf16 v[16:19], v[12:15], v[90:93], v[16:19]
	v_lshlrev_b32_e32 v30, 16, v34
	v_and_b32_e32 v31, 0xffff0000, v34
	v_lshlrev_b32_e32 v32, 16, v35
	v_and_b32_e32 v33, 0xffff0000, v35
	v_add_u32_e32 v34, v98, v2
	s_nop 2
	v_cvt_pk_bf16_f32 v16, v16, v17
	v_cvt_pk_bf16_f32 v17, v18, v19
	ds_write_b64 v89, v[16:17]
	ds_read_b128 v[16:19], v102
	ds_read_b128 v[90:93], v103 offset:64
	s_waitcnt lgkmcnt(1)
	v_mfma_f32_16x16x32_bf16 v[16:19], v[8:11], v[16:19], v[30:33]
	v_add3_u32 v35, s0, v2, v0
	s_nop 1
	v_lshlrev_b32_e32 v30, 16, v94
	v_and_b32_e32 v31, 0xffff0000, v94
	s_waitcnt lgkmcnt(0)
	v_mfma_f32_16x16x32_bf16 v[16:19], v[12:15], v[90:93], v[16:19]
	v_lshlrev_b32_e32 v32, 16, v95
	v_and_b32_e32 v33, 0xffff0000, v95
	v_add_u32_e32 v104, v98, v1
	v_add3_u32 v105, s0, v1, v0
	s_add_i32 s0, 0, 0x19600
	s_nop 2
	v_cvt_pk_bf16_f32 v16, v16, v17
	v_cvt_pk_bf16_f32 v17, v18, v19
	ds_write_b64 v89, v[16:17] offset:2304
	ds_read_b128 v[16:19], v34
	ds_read_b128 v[90:93], v35 offset:64
	s_waitcnt lgkmcnt(1)
	v_mfma_f32_16x16x32_bf16 v[16:19], v[8:11], v[16:19], v[30:33]
	s_nop 2
	v_lshlrev_b32_e32 v30, 16, v96
	v_and_b32_e32 v31, 0xffff0000, v96
	v_lshlrev_b32_e32 v32, 16, v97
	s_waitcnt lgkmcnt(0)
	v_mfma_f32_16x16x32_bf16 v[16:19], v[12:15], v[90:93], v[16:19]
	v_and_b32_e32 v33, 0xffff0000, v97
	s_nop 6
	v_cvt_pk_bf16_f32 v16, v16, v17
	v_cvt_pk_bf16_f32 v17, v18, v19
	ds_write_b64 v89, v[16:17] offset:4608
	ds_read_b128 v[16:19], v104
	ds_read_b128 v[90:93], v105 offset:64
	s_waitcnt lgkmcnt(1)
	v_mfma_f32_16x16x32_bf16 v[8:11], v[8:11], v[16:19], v[30:33]
	s_waitcnt lgkmcnt(0)
	v_mfma_f32_16x16x32_bf16 v[8:11], v[12:15], v[90:93], v[8:11]
	s_nop 7
	v_cvt_pk_bf16_f32 v8, v8, v9
	v_cvt_pk_bf16_f32 v9, v10, v11
	ds_write_b64 v89, v[8:9] offset:6912
	ds_read_b128 v[8:11], v29 offset:27648
	ds_read_b128 v[12:15], v29 offset:27712
	ds_read_b128 v[16:19], v99
	ds_read_b128 v[30:33], v99 offset:64
	ds_read_b128 v[90:93], v29 offset:64512
	ds_read_b128 v[94:97], v29 offset:64576
	s_waitcnt lgkmcnt(3)
	v_mfma_f32_16x16x32_bf16 v[16:19], v[8:11], v[16:19], 0
	v_add_u32_e32 v89, s0, v0
	v_mad_u32_u24 v98, v7, s76, v89
	v_add3_u32 v29, s70, v5, v6
	s_waitcnt lgkmcnt(2)
	v_mfma_f32_16x16x32_bf16 v[16:19], v[12:15], v[30:33], v[16:19]
	ds_read_b128 v[30:33], v98
	ds_read_b128 v[98:101], v98 offset:64
	s_waitcnt lgkmcnt(1)
	v_mfma_f32_16x16x32_bf16 v[16:19], v[90:93], v[30:33], v[16:19]
	s_waitcnt lgkmcnt(0)
	v_mfma_f32_16x16x32_bf16 v[16:19], v[94:97], v[98:101], v[16:19]
	v_add_u32_e32 v98, v89, v4
	s_nop 6
	v_cvt_pk_bf16_f32 v16, v16, v17
	v_cvt_pk_bf16_f32 v17, v18, v19
	ds_write_b64 v29, v[16:17]
	ds_read_b128 v[16:19], v102
	ds_read_b128 v[30:33], v103 offset:64
	s_waitcnt lgkmcnt(1)
	v_mfma_f32_16x16x32_bf16 v[16:19], v[8:11], v[16:19], 0
	s_waitcnt lgkmcnt(0)
	v_mfma_f32_16x16x32_bf16 v[16:19], v[12:15], v[30:33], v[16:19]
	ds_read_b128 v[30:33], v98
	v_add3_u32 v98, s0, v4, v0
	ds_read_b128 v[98:101], v98 offset:64
	s_waitcnt lgkmcnt(1)
	v_mfma_f32_16x16x32_bf16 v[16:19], v[90:93], v[30:33], v[16:19]
	s_waitcnt lgkmcnt(0)
	v_mfma_f32_16x16x32_bf16 v[16:19], v[94:97], v[98:101], v[16:19]
	s_nop 7
	v_cvt_pk_bf16_f32 v16, v16, v17
	v_cvt_pk_bf16_f32 v17, v18, v19
	ds_write_b64 v29, v[16:17] offset:2304
	ds_read_b128 v[16:19], v34
	ds_read_b128 v[30:33], v35 offset:64
	s_waitcnt lgkmcnt(1)
	v_mfma_f32_16x16x32_bf16 v[16:19], v[8:11], v[16:19], 0
	v_add_u32_e32 v34, v89, v2
	s_waitcnt lgkmcnt(0)
	v_mfma_f32_16x16x32_bf16 v[16:19], v[12:15], v[30:33], v[16:19]
	ds_read_b128 v[30:33], v34
	v_add3_u32 v34, s0, v2, v0
	ds_read_b128 v[98:101], v34 offset:64
	s_waitcnt lgkmcnt(1)
	v_mfma_f32_16x16x32_bf16 v[16:19], v[90:93], v[30:33], v[16:19]
	s_waitcnt lgkmcnt(0)
	v_mfma_f32_16x16x32_bf16 v[16:19], v[94:97], v[98:101], v[16:19]
	s_nop 7
	v_cvt_pk_bf16_f32 v16, v16, v17
	v_cvt_pk_bf16_f32 v17, v18, v19
	ds_write_b64 v29, v[16:17] offset:4608
	ds_read_b128 v[16:19], v104
	ds_read_b128 v[30:33], v105 offset:64
	s_waitcnt lgkmcnt(1)
	v_mfma_f32_16x16x32_bf16 v[8:11], v[8:11], v[16:19], 0
	v_add_u32_e32 v16, v89, v1
	s_waitcnt lgkmcnt(0)
	v_mfma_f32_16x16x32_bf16 v[8:11], v[12:15], v[30:33], v[8:11]
	ds_read_b128 v[12:15], v16
	v_add3_u32 v16, s0, v1, v0
	ds_read_b128 v[16:19], v16 offset:64
	s_waitcnt lgkmcnt(1)
	v_mfma_f32_16x16x32_bf16 v[8:11], v[90:93], v[12:15], v[8:11]
	s_mov_b64 s[0:1], 0
	s_waitcnt lgkmcnt(0)
	v_mfma_f32_16x16x32_bf16 v[8:11], v[94:97], v[16:19], v[8:11]
	s_nop 7
	v_cvt_pk_bf16_f32 v8, v8, v9
	v_cvt_pk_bf16_f32 v9, v10, v11
	ds_write_b64 v29, v[8:9] offset:6912
